# P0: first 4-row step of the x->bf16 pass loaded during the S5 table build (HBM-bound step overlapped with the compute-bound build)
# speedup vs baseline: 1.0030x; 1.0030x over previous
; #define INP(k) ((const float*)(GAS const float*)KARG64(8 * (k)))
; #define R1 ((float*)(WSP() + WS_R1))
; __device__ __forceinline__ void ssm_tables(int g, int part, LAS float* L, bf16* __restrict__ TE, bf16* __restrict__ FT, float* __restrict__ LAM16) {
;     ...
;         if (k == 0 && c == c2) s += INP(11)[g * 16 + c];
;         Kt[tid] = s;
;     }
;     __syncthreads();
; __global__ void __launch_bounds__(NWAVES * 64, 2) hybrid_fwd(Params P) {
;     ...
;         for (int m0 = gw * 4; m0 < MAINR + NMETA; m0 += NGW * 4) {
;             const float* src[4]; bf16* dst[4]; float* rr[4];
; #pragma unroll
;             for (int r = 0; r < 4; ++r) { const int m = m0 + r; src[r] = m < MAINR ? INP(0) + (size_t)m * 1024 : INP(1) + (size_t)(m - MAINR) * 1024; dst[r] = XB + (size_t)m * 1024; rr[r] = R1 + m; }
;             rows_to_bf16<4>(src, dst, rr, lane);
.LBB0_18:
	s_or_b64 exec, exec, s[16:17]
	s_add_u32 s14, s14, 0x1e00000
	s_addc_u32 s15, s15, 0
	ds_write_b32 v1, v2 offset:25600
	s_lshl_b32 s35, s12, 8
	s_mov_b64 s[12:13], 0
	v_mov_b32_e32 v2, v218
	s_waitcnt lgkmcnt(0)
	s_barrier
	s_mov_b64 s[68:69], exec
	s_mov_b64 exec, -1
	s_load_dwordx2 s[60:61], s[0:1], 0x0
	v_lshlrev_b32_e32 v91, 4, v174
	s_lshl_b32 s62, s57, 14
	s_waitcnt lgkmcnt(0)
	s_add_u32 s60, s60, s62
	s_addc_u32 s61, s61, 0
	s_add_u32 s62, s60, 0x1000
	s_addc_u32 s63, s61, 0
	s_add_u32 s64, s60, 0x2000
	s_addc_u32 s65, s61, 0
	s_add_u32 s66, s60, 0x3000
	s_addc_u32 s67, s61, 0
	global_load_dwordx4 v[160:163], v91, s[60:61] nt
	global_load_dwordx4 v[156:159], v91, s[60:61] offset:1024 nt
	global_load_dwordx4 v[152:155], v91, s[60:61] offset:2048 nt
	global_load_dwordx4 v[148:151], v91, s[60:61] offset:3072 nt
	global_load_dwordx4 v[144:147], v91, s[62:63] nt
	global_load_dwordx4 v[140:143], v91, s[62:63] offset:1024 nt
	global_load_dwordx4 v[136:139], v91, s[62:63] offset:2048 nt
	global_load_dwordx4 v[132:135], v91, s[62:63] offset:3072 nt
	global_load_dwordx4 v[128:131], v91, s[64:65] nt
	global_load_dwordx4 v[124:127], v91, s[64:65] offset:1024 nt
	global_load_dwordx4 v[120:123], v91, s[64:65] offset:2048 nt
	global_load_dwordx4 v[116:119], v91, s[64:65] offset:3072 nt
	global_load_dwordx4 v[112:115], v91, s[66:67] nt
	global_load_dwordx4 v[108:111], v91, s[66:67] offset:1024 nt
	global_load_dwordx4 v[104:107], v91, s[66:67] offset:2048 nt
	global_load_dwordx4 v[100:103], v91, s[66:67] offset:3072 nt
	s_mov_b32 s59, 1
	s_mov_b64 exec, s[68:69]
	s_branch .LBB0_21

; __device__ __forceinline__ unsigned cvtpk(float lo, float hi) { f32x2 v = {lo, hi}; bf16x2_t b = __builtin_convertvector(v, bf16x2_t); return __builtin_bit_cast(unsigned, b); }
; __device__ __forceinline__ float sq4(f32x4 v) { return (v[0] * v[0] + v[1] * v[1]) + (v[2] * v[2] + v[3] * v[3]); }
; #define INP(k) ((const float*)(GAS const float*)KARG64(8 * (k)))
; #define R1 ((float*)(WSP() + WS_R1))
; template <int NR> __device__ __forceinline__ void rows_to_bf16(const float* const* src, bf16* const* dst, float* const* r1, int lane) {
;     f32x4 v[NR][4];
; #pragma unroll
;     for (int r = 0; r < NR; ++r)
; #pragma unroll
;         for (int j = 0; j < 4; ++j) v[r][j] = __builtin_nontemporal_load((const f32x4*)src[r] + lane + 64 * j);
; #pragma unroll
;     for (int r = 0; r < NR; ++r) {
;         float s = 0.f;
; #pragma unroll
;         for (int j = 0; j < 4; ++j) s += sq4(v[r][j]);
;         s = wave_sum(s);
;         if (lane == 0) *r1[r] = __builtin_amdgcn_rsqf(s * (1.f / 1024.f) + EPS);
;         u32x2* o8 = (u32x2*)dst[r] + lane;
; #pragma unroll
;         for (int j = 0; j < 4; ++j) { u32x2 w; w.x = cvtpk(v[r][j][0], v[r][j][1]); w.y = cvtpk(v[r][j][2], v[r][j][3]); o8[64 * j] = w; }
;     }
; __global__ void __launch_bounds__(NWAVES * 64, 2) hybrid_fwd(Params P) {
;     ...
;         for (int m0 = gw * 4; m0 < MAINR + NMETA; m0 += NGW * 4) {
;             const float* src[4]; bf16* dst[4]; float* rr[4];
; #pragma unroll
;             for (int r = 0; r < 4; ++r) { const int m = m0 + r; src[r] = m < MAINR ? INP(0) + (size_t)m * 1024 : INP(1) + (size_t)(m - MAINR) * 1024; dst[r] = XB + (size_t)m * 1024; rr[r] = R1 + m; }
;             rows_to_bf16<4>(src, dst, rr, lane);
;         }
.LBB0_79:
	s_mov_b64 s[26:27], s[0:1]
	s_mov_b64 s[52:53], s[0:1]
	s_load_dwordx2 s[26:27], s[26:27], 0xf0
	s_cmp_eq_u32 s59, 0
	s_cbranch_scc1 .Lrows_ld
	s_mov_b32 s59, 0
	s_waitcnt vmcnt(0) lgkmcnt(0)
	v_mov_b64_e32 v[2:3], v[100:101]
	v_mov_b64_e32 v[4:5], v[102:103]
	v_mov_b64_e32 v[6:7], v[104:105]
	v_mov_b64_e32 v[8:9], v[106:107]
	v_mov_b64_e32 v[10:11], v[108:109]
	v_mov_b64_e32 v[12:13], v[110:111]
	v_mov_b64_e32 v[14:15], v[112:113]
	v_mov_b64_e32 v[16:17], v[114:115]
	v_mov_b64_e32 v[18:19], v[116:117]
	v_mov_b64_e32 v[20:21], v[118:119]
	v_mov_b64_e32 v[22:23], v[120:121]
	v_mov_b64_e32 v[24:25], v[122:123]
	v_mov_b64_e32 v[26:27], v[124:125]
	v_mov_b64_e32 v[28:29], v[126:127]
	v_mov_b64_e32 v[30:31], v[128:129]
	v_mov_b64_e32 v[32:33], v[130:131]
	v_mov_b64_e32 v[34:35], v[132:133]
	v_mov_b64_e32 v[36:37], v[134:135]
	v_mov_b64_e32 v[38:39], v[136:137]
	v_mov_b64_e32 v[40:41], v[138:139]
	v_mov_b64_e32 v[42:43], v[140:141]
	v_mov_b64_e32 v[44:45], v[142:143]
	v_mov_b64_e32 v[46:47], v[144:145]
	v_mov_b64_e32 v[48:49], v[146:147]
	v_mov_b64_e32 v[50:51], v[148:149]
	v_mov_b64_e32 v[52:53], v[150:151]
	v_mov_b64_e32 v[54:55], v[152:153]
	v_mov_b64_e32 v[56:57], v[154:155]
	v_mov_b64_e32 v[58:59], v[156:157]
	v_mov_b64_e32 v[60:61], v[158:159]
	v_mov_b64_e32 v[62:63], v[160:161]
	v_mov_b64_e32 v[64:65], v[162:163]
	s_branch .Lrows_go
.Lrows_ld:
	global_load_dwordx4 v[62:65], v1, s[44:45] nt
	global_load_dwordx4 v[58:61], v1, s[44:45] offset:1024 nt
	global_load_dwordx4 v[54:57], v1, s[44:45] offset:2048 nt
	global_load_dwordx4 v[50:53], v1, s[44:45] offset:3072 nt
	global_load_dwordx4 v[46:49], v1, s[48:49] nt
	global_load_dwordx4 v[42:45], v1, s[48:49] offset:1024 nt
	global_load_dwordx4 v[38:41], v1, s[48:49] offset:2048 nt
	global_load_dwordx4 v[34:37], v1, s[48:49] offset:3072 nt
	global_load_dwordx4 v[30:33], v1, s[50:51] nt
	global_load_dwordx4 v[26:29], v1, s[50:51] offset:1024 nt
	s_waitcnt lgkmcnt(0)
	global_load_dwordx4 v[22:25], v1, s[50:51] offset:2048 nt
	global_load_dwordx4 v[18:21], v1, s[50:51] offset:3072 nt
	global_load_dwordx4 v[14:17], v1, s[54:55] nt
	global_load_dwordx4 v[10:13], v1, s[54:55] offset:1024 nt
	global_load_dwordx4 v[6:9], v1, s[54:55] offset:2048 nt
	global_load_dwordx4 v[2:5], v1, s[54:55] offset:3072 nt
.Lrows_go:
	v_cmp_lt_i32_e32 vcc, v72, v71
	s_load_dwordx2 s[44:45], s[52:53], 0xf0
	s_waitcnt vmcnt(15)
	v_mul_f32_e32 v80, v65, v65
	v_cndmask_b32_e32 v68, v70, v72, vcc
	v_lshlrev_b32_e32 v79, 2, v68
	v_mul_f32_e32 v68, v63, v63
	s_waitcnt vmcnt(14)
	v_mul_f32_e32 v81, v59, v59
	v_mul_f32_e32 v82, v61, v61
	s_waitcnt vmcnt(13)
	v_mul_f32_e32 v83, v55, v55
	v_mul_f32_e32 v84, v57, v57
	v_fmac_f32_e32 v68, v62, v62
	v_fmac_f32_e32 v80, v64, v64
	v_fmac_f32_e32 v81, v58, v58
	v_fmac_f32_e32 v82, v60, v60
	s_waitcnt vmcnt(12)
	v_mul_f32_e32 v85, v51, v51
	v_mul_f32_e32 v86, v53, v53
	v_fmac_f32_e32 v83, v54, v54
	v_fmac_f32_e32 v84, v56, v56
	v_add_f32_e32 v68, v68, v80
	v_add_f32_e32 v80, v81, v82
	v_fmac_f32_e32 v85, v50, v50
	v_fmac_f32_e32 v86, v52, v52
	v_add_f32_e32 v81, v83, v84
	v_add_f32_e32 v68, v68, v80
	v_add_f32_e32 v68, v68, v81
	v_add_f32_e32 v80, v85, v86
	v_add_f32_e32 v68, v68, v80
	ds_bpermute_b32 v80, v79, v68
	v_cmp_lt_i32_e32 vcc, v73, v71
	s_waitcnt lgkmcnt(0)
	v_add_f32_e32 v68, v68, v80
	v_cndmask_b32_e32 v81, v70, v73, vcc
	v_lshlrev_b32_e32 v84, 2, v81
	ds_bpermute_b32 v80, v84, v68
	v_cmp_lt_i32_e32 vcc, v74, v71
	s_waitcnt lgkmcnt(0)
	v_add_f32_e32 v68, v68, v80
	v_cndmask_b32_e32 v81, v70, v74, vcc
	v_lshlrev_b32_e32 v82, 2, v81
	ds_bpermute_b32 v80, v82, v68
	v_cmp_lt_i32_e32 vcc, v75, v71
	s_waitcnt lgkmcnt(0)
	v_add_f32_e32 v68, v68, v80
	v_cndmask_b32_e32 v81, v70, v75, vcc
	v_lshlrev_b32_e32 v83, 2, v81
	ds_bpermute_b32 v81, v83, v68
	v_cmp_lt_i32_e32 vcc, v76, v71
	s_waitcnt lgkmcnt(0)
	v_add_f32_e32 v68, v68, v81
	v_cndmask_b32_e32 v80, v70, v76, vcc
	v_lshlrev_b32_e32 v80, 2, v80
	ds_bpermute_b32 v85, v80, v68
	v_cmp_lt_i32_e32 vcc, v77, v71
	s_waitcnt lgkmcnt(0)
	v_add_f32_e32 v68, v68, v85
	v_cndmask_b32_e32 v81, v70, v77, vcc
	v_lshlrev_b32_e32 v81, 2, v81
	ds_bpermute_b32 v85, v81, v68
	s_and_saveexec_b64 s[38:39], s[4:5]
	s_xor_b64 s[48:49], exec, s[38:39]
	s_cbranch_execz .LBB0_81
	s_waitcnt lgkmcnt(0)
	v_add_f32_e32 v68, v68, v85
	v_fmamk_f32 v68, v68, 0x3a800000, v78
	v_rsq_f32_e32 v68, v68
	s_lshl_b64 s[38:39], s[34:35], 2
	s_add_u32 s38, s46, s38
	s_addc_u32 s39, s47, s39
	global_store_dword v69, v68, s[38:39]
